# baseline (speedup 1.0000x reference)
; __device__ __forceinline__ u32 pack2(float a, float b) { return (u32)f2bf(a) | ((u32)f2bf(b) << 16); }
; __device__ __forceinline__ float sigmoidf_(float x) { return __builtin_amdgcn_rcpf(1.f + __expf(-x)); }
; __device__ __forceinline__ void gemm_tile(const GemmArgs& ga, int wgid, int next_wgid, bool prefetched, u16* shm, unsigned char* ws, int wv_) {
;     ...
;   if (epi == EPI_SWIGLU) {
;     const int oc = pn * HALF + (wc * 16 + fr) * 2;
;     float sc[2][4][4];
;     _Pragma("unroll") for (int ai = 0; ai < 2; ++ai)
;       _Pragma("unroll") for (int m = 0; m < 4; ++m)
;         _Pragma("unroll") for (int j = 0; j < 4; ++j) sc[ai][m][j] = e_ss[rbase + ai * HALF + m * 16 + j];
;     _Pragma("unroll") for (int ai = 0; ai < 2; ++ai)
;       _Pragma("unroll") for (int m = 0; m < 4; ++m)
;         _Pragma("unroll") for (int j = 0; j < 4; ++j) {
;           int row = rbase + ai * HALF + m * 16 + j;
;           float s = rsqrtf(sc[ai][m][j] * (1.f / D_) + 1e-6f);
;           float h2[2];
;           _Pragma("unroll") for (int n = 0; n < 2; ++n) {
;             float a1 = acc[ai][0][m][n][j] * s, a3 = acc[ai][1][m][n][j] * s;
;             h2[n] = a1 * sigmoidf_(a1) * a3;
;           }
;           *(u32*)(e_outb + (size_t)row * F_ + oc) = pack2(h2[0], h2[1]);
;         }
.Lsswd_s:
	v_pk_fma_f32 v[0:1], v[208:209], s[12:13], v[130:131] op_sel_hi:[1,0,0]
	v_add_u32_e32 v8, 0, v168
	v_add_u32_e32 v9, 1, v168
	v_rsq_f32_e32 v0, v0
	v_rsq_f32_e32 v1, v1
	v_mad_i64_i32 v[10:11], s[2:3], v8, s8, v[128:129]
	v_mad_i64_i32 v[2:3], s[2:3], v9, s8, v[128:129]
	v_pk_mul_f32 v[16:17], v[116:117], v[0:1]
	v_pk_mul_f32 v[18:19], v[112:113], v[0:1]
	v_pk_mul_f32 v[136:137], v[124:125], v[0:1]
	v_pk_mul_f32 v[138:139], v[120:121], v[0:1]
	v_mul_f32_e32 v140, 0xbfb8aa3b, v16
	v_mul_f32_e32 v141, 0xbfb8aa3b, v17
	v_mul_f32_e32 v142, 0xbfb8aa3b, v18
	v_mul_f32_e32 v143, 0xbfb8aa3b, v19
	v_exp_f32_e32 v140, v140
	v_exp_f32_e32 v141, v141
	v_exp_f32_e32 v142, v142
	v_exp_f32_e32 v143, v143
	v_add_f32_e32 v140, 1.0, v140
	v_add_f32_e32 v141, 1.0, v141
	v_add_f32_e32 v142, 1.0, v142
	v_add_f32_e32 v143, 1.0, v143
	v_rcp_f32_e32 v140, v140
	v_rcp_f32_e32 v141, v141
	v_rcp_f32_e32 v142, v142
	v_rcp_f32_e32 v143, v143
	s_nop 0
	v_pk_mul_f32 v[16:17], v[16:17], v[140:141]
	v_pk_mul_f32 v[18:19], v[18:19], v[142:143]
	v_pk_mul_f32 v[16:17], v[136:137], v[16:17]
	v_pk_mul_f32 v[18:19], v[138:139], v[18:19]
	v_cvt_pk_bf16_f32 v8, v16, v18
	v_cvt_pk_bf16_f32 v9, v17, v19
	global_store_dword v[10:11], v8, off
	global_store_dword v[2:3], v9, off
	v_pk_fma_f32 v[0:1], v[210:211], s[12:13], v[130:131] op_sel_hi:[1,0,0]
	v_add_u32_e32 v8, 2, v168
	v_add_u32_e32 v9, 3, v168
	v_rsq_f32_e32 v0, v0
	v_rsq_f32_e32 v1, v1
	v_mad_i64_i32 v[10:11], s[2:3], v8, s8, v[128:129]
	v_mad_i64_i32 v[2:3], s[2:3], v9, s8, v[128:129]
	v_pk_mul_f32 v[16:17], v[118:119], v[0:1]
	v_pk_mul_f32 v[18:19], v[114:115], v[0:1]
	v_pk_mul_f32 v[136:137], v[126:127], v[0:1]
	v_pk_mul_f32 v[138:139], v[122:123], v[0:1]
	v_mul_f32_e32 v140, 0xbfb8aa3b, v16
	v_mul_f32_e32 v141, 0xbfb8aa3b, v17
	v_mul_f32_e32 v142, 0xbfb8aa3b, v18
	v_mul_f32_e32 v143, 0xbfb8aa3b, v19
	v_exp_f32_e32 v140, v140
	v_exp_f32_e32 v141, v141
	v_exp_f32_e32 v142, v142
	v_exp_f32_e32 v143, v143
	v_add_f32_e32 v140, 1.0, v140
	v_add_f32_e32 v141, 1.0, v141
	v_add_f32_e32 v142, 1.0, v142
	v_add_f32_e32 v143, 1.0, v143
	v_rcp_f32_e32 v140, v140
	v_rcp_f32_e32 v141, v141
	v_rcp_f32_e32 v142, v142
	v_rcp_f32_e32 v143, v143
	s_nop 0
	v_pk_mul_f32 v[16:17], v[16:17], v[140:141]
	v_pk_mul_f32 v[18:19], v[18:19], v[142:143]
	v_pk_mul_f32 v[16:17], v[136:137], v[16:17]
	v_pk_mul_f32 v[18:19], v[138:139], v[18:19]
	v_cvt_pk_bf16_f32 v8, v16, v18
	v_cvt_pk_bf16_f32 v9, v17, v19
	global_store_dword v[10:11], v8, off
	global_store_dword v[2:3], v9, off
	v_pk_fma_f32 v[0:1], v[212:213], s[12:13], v[130:131] op_sel_hi:[1,0,0]
	v_add_u32_e32 v8, 16, v168
	v_add_u32_e32 v9, 17, v168
	v_rsq_f32_e32 v0, v0
	v_rsq_f32_e32 v1, v1
	v_mad_i64_i32 v[10:11], s[2:3], v8, s8, v[128:129]
	v_mad_i64_i32 v[2:3], s[2:3], v9, s8, v[128:129]
	v_pk_mul_f32 v[16:17], v[100:101], v[0:1]
	v_pk_mul_f32 v[18:19], v[96:97], v[0:1]
	v_pk_mul_f32 v[136:137], v[108:109], v[0:1]
	v_pk_mul_f32 v[138:139], v[104:105], v[0:1]
	v_mul_f32_e32 v140, 0xbfb8aa3b, v16
	v_mul_f32_e32 v141, 0xbfb8aa3b, v17
	v_mul_f32_e32 v142, 0xbfb8aa3b, v18
	v_mul_f32_e32 v143, 0xbfb8aa3b, v19
	v_exp_f32_e32 v140, v140
	v_exp_f32_e32 v141, v141
	v_exp_f32_e32 v142, v142
	v_exp_f32_e32 v143, v143
	v_add_f32_e32 v140, 1.0, v140
	v_add_f32_e32 v141, 1.0, v141
	v_add_f32_e32 v142, 1.0, v142
	v_add_f32_e32 v143, 1.0, v143
	v_rcp_f32_e32 v140, v140
	v_rcp_f32_e32 v141, v141
	v_rcp_f32_e32 v142, v142
	v_rcp_f32_e32 v143, v143
	s_nop 0
	v_pk_mul_f32 v[16:17], v[16:17], v[140:141]
	v_pk_mul_f32 v[18:19], v[18:19], v[142:143]
	v_pk_mul_f32 v[16:17], v[136:137], v[16:17]
	v_pk_mul_f32 v[18:19], v[138:139], v[18:19]
	v_cvt_pk_bf16_f32 v8, v16, v18
	v_cvt_pk_bf16_f32 v9, v17, v19
	global_store_dword v[10:11], v8, off
	global_store_dword v[2:3], v9, off
	v_pk_fma_f32 v[0:1], v[214:215], s[12:13], v[130:131] op_sel_hi:[1,0,0]
	v_add_u32_e32 v8, 18, v168
	v_add_u32_e32 v9, 19, v168
	v_rsq_f32_e32 v0, v0
	v_rsq_f32_e32 v1, v1
	v_mad_i64_i32 v[10:11], s[2:3], v8, s8, v[128:129]
	v_mad_i64_i32 v[2:3], s[2:3], v9, s8, v[128:129]
	v_pk_mul_f32 v[16:17], v[102:103], v[0:1]
	v_pk_mul_f32 v[18:19], v[98:99], v[0:1]
	v_pk_mul_f32 v[136:137], v[110:111], v[0:1]
	v_pk_mul_f32 v[138:139], v[106:107], v[0:1]
	v_mul_f32_e32 v140, 0xbfb8aa3b, v16
	v_mul_f32_e32 v141, 0xbfb8aa3b, v17
	v_mul_f32_e32 v142, 0xbfb8aa3b, v18
	v_mul_f32_e32 v143, 0xbfb8aa3b, v19
	v_exp_f32_e32 v140, v140
	v_exp_f32_e32 v141, v141
	v_exp_f32_e32 v142, v142
	v_exp_f32_e32 v143, v143
	v_add_f32_e32 v140, 1.0, v140
	v_add_f32_e32 v141, 1.0, v141
	v_add_f32_e32 v142, 1.0, v142
	v_add_f32_e32 v143, 1.0, v143
	v_rcp_f32_e32 v140, v140
	v_rcp_f32_e32 v141, v141
	v_rcp_f32_e32 v142, v142
	v_rcp_f32_e32 v143, v143
	s_nop 0
	v_pk_mul_f32 v[16:17], v[16:17], v[140:141]
	v_pk_mul_f32 v[18:19], v[18:19], v[142:143]
	v_pk_mul_f32 v[16:17], v[136:137], v[16:17]
	v_pk_mul_f32 v[18:19], v[138:139], v[18:19]
	v_cvt_pk_bf16_f32 v8, v16, v18
	v_cvt_pk_bf16_f32 v9, v17, v19
	global_store_dword v[10:11], v8, off
	global_store_dword v[2:3], v9, off
	v_pk_fma_f32 v[0:1], v[216:217], s[12:13], v[130:131] op_sel_hi:[1,0,0]
	v_add_u32_e32 v8, 32, v168
	v_add_u32_e32 v9, 33, v168
	v_rsq_f32_e32 v0, v0
	v_rsq_f32_e32 v1, v1
	v_mad_i64_i32 v[10:11], s[2:3], v8, s8, v[128:129]
	v_mad_i64_i32 v[2:3], s[2:3], v9, s8, v[128:129]
	v_pk_mul_f32 v[16:17], v[84:85], v[0:1]
	v_pk_mul_f32 v[18:19], v[80:81], v[0:1]
	v_pk_mul_f32 v[136:137], v[92:93], v[0:1]
	v_pk_mul_f32 v[138:139], v[88:89], v[0:1]
	v_mul_f32_e32 v140, 0xbfb8aa3b, v16
	v_mul_f32_e32 v141, 0xbfb8aa3b, v17
	v_mul_f32_e32 v142, 0xbfb8aa3b, v18
	v_mul_f32_e32 v143, 0xbfb8aa3b, v19
	v_exp_f32_e32 v140, v140
; __device__ __forceinline__ u32 pack2(float a, float b) { return (u32)f2bf(a) | ((u32)f2bf(b) << 16); }
; __device__ __forceinline__ float sigmoidf_(float x) { return __builtin_amdgcn_rcpf(1.f + __expf(-x)); }
; __device__ __forceinline__ void gemm_tile(const GemmArgs& ga, int wgid, int next_wgid, bool prefetched, u16* shm, unsigned char* ws, int wv_) {
;     ...
;   if (epi == EPI_SWIGLU) {
;     const int oc = pn * HALF + (wc * 16 + fr) * 2;
;     float sc[2][4][4];
;     _Pragma("unroll") for (int ai = 0; ai < 2; ++ai)
;       _Pragma("unroll") for (int m = 0; m < 4; ++m)
;         _Pragma("unroll") for (int j = 0; j < 4; ++j) sc[ai][m][j] = e_ss[rbase + ai * HALF + m * 16 + j];
;     _Pragma("unroll") for (int ai = 0; ai < 2; ++ai)
;       _Pragma("unroll") for (int m = 0; m < 4; ++m)
;         _Pragma("unroll") for (int j = 0; j < 4; ++j) {
;           int row = rbase + ai * HALF + m * 16 + j;
;           float s = rsqrtf(sc[ai][m][j] * (1.f / D_) + 1e-6f);
;           float h2[2];
;           _Pragma("unroll") for (int n = 0; n < 2; ++n) {
;             float a1 = acc[ai][0][m][n][j] * s, a3 = acc[ai][1][m][n][j] * s;
;             h2[n] = a1 * sigmoidf_(a1) * a3;
;           }
;           *(u32*)(e_outb + (size_t)row * F_ + oc) = pack2(h2[0], h2[1]);
;         }
	v_exp_f32_e32 v141, v141
	v_exp_f32_e32 v142, v142
	v_exp_f32_e32 v143, v143
	v_add_f32_e32 v140, 1.0, v140
	v_add_f32_e32 v141, 1.0, v141
	v_add_f32_e32 v142, 1.0, v142
	v_add_f32_e32 v143, 1.0, v143
	v_rcp_f32_e32 v140, v140
	v_rcp_f32_e32 v141, v141
	v_rcp_f32_e32 v142, v142
	v_rcp_f32_e32 v143, v143
	s_nop 0
	v_pk_mul_f32 v[16:17], v[16:17], v[140:141]
	v_pk_mul_f32 v[18:19], v[18:19], v[142:143]
	v_pk_mul_f32 v[16:17], v[136:137], v[16:17]
	v_pk_mul_f32 v[18:19], v[138:139], v[18:19]
	v_cvt_pk_bf16_f32 v8, v16, v18
	v_cvt_pk_bf16_f32 v9, v17, v19
	global_store_dword v[10:11], v8, off
	global_store_dword v[2:3], v9, off
	v_pk_fma_f32 v[0:1], v[218:219], s[12:13], v[130:131] op_sel_hi:[1,0,0]
	v_add_u32_e32 v8, 34, v168
	v_add_u32_e32 v9, 35, v168
	v_rsq_f32_e32 v0, v0
	v_rsq_f32_e32 v1, v1
	v_mad_i64_i32 v[10:11], s[2:3], v8, s8, v[128:129]
	v_mad_i64_i32 v[2:3], s[2:3], v9, s8, v[128:129]
	v_pk_mul_f32 v[16:17], v[86:87], v[0:1]
	v_pk_mul_f32 v[18:19], v[82:83], v[0:1]
	v_pk_mul_f32 v[136:137], v[94:95], v[0:1]
	v_pk_mul_f32 v[138:139], v[90:91], v[0:1]
	v_mul_f32_e32 v140, 0xbfb8aa3b, v16
	v_mul_f32_e32 v141, 0xbfb8aa3b, v17
	v_mul_f32_e32 v142, 0xbfb8aa3b, v18
	v_mul_f32_e32 v143, 0xbfb8aa3b, v19
	v_exp_f32_e32 v140, v140
	v_exp_f32_e32 v141, v141
	v_exp_f32_e32 v142, v142
	v_exp_f32_e32 v143, v143
	v_add_f32_e32 v140, 1.0, v140
	v_add_f32_e32 v141, 1.0, v141
	v_add_f32_e32 v142, 1.0, v142
	v_add_f32_e32 v143, 1.0, v143
	v_rcp_f32_e32 v140, v140
	v_rcp_f32_e32 v141, v141
	v_rcp_f32_e32 v142, v142
	v_rcp_f32_e32 v143, v143
	s_nop 0
	v_pk_mul_f32 v[16:17], v[16:17], v[140:141]
	v_pk_mul_f32 v[18:19], v[18:19], v[142:143]
	v_pk_mul_f32 v[16:17], v[136:137], v[16:17]
	v_pk_mul_f32 v[18:19], v[138:139], v[18:19]
	v_cvt_pk_bf16_f32 v8, v16, v18
	v_cvt_pk_bf16_f32 v9, v17, v19
	global_store_dword v[10:11], v8, off
	global_store_dword v[2:3], v9, off
	v_pk_fma_f32 v[0:1], v[220:221], s[12:13], v[130:131] op_sel_hi:[1,0,0]
	v_add_u32_e32 v8, 48, v168
	v_add_u32_e32 v9, 49, v168
	v_rsq_f32_e32 v0, v0
	v_rsq_f32_e32 v1, v1
	v_mad_i64_i32 v[10:11], s[2:3], v8, s8, v[128:129]
	v_mad_i64_i32 v[2:3], s[2:3], v9, s8, v[128:129]
	v_pk_mul_f32 v[16:17], v[68:69], v[0:1]
	v_pk_mul_f32 v[18:19], v[64:65], v[0:1]
	v_pk_mul_f32 v[136:137], v[76:77], v[0:1]
	v_pk_mul_f32 v[138:139], v[72:73], v[0:1]
	v_mul_f32_e32 v140, 0xbfb8aa3b, v16
	v_mul_f32_e32 v141, 0xbfb8aa3b, v17
	v_mul_f32_e32 v142, 0xbfb8aa3b, v18
	v_mul_f32_e32 v143, 0xbfb8aa3b, v19
	v_exp_f32_e32 v140, v140
	v_exp_f32_e32 v141, v141
	v_exp_f32_e32 v142, v142
	v_exp_f32_e32 v143, v143
	v_add_f32_e32 v140, 1.0, v140
	v_add_f32_e32 v141, 1.0, v141
	v_add_f32_e32 v142, 1.0, v142
	v_add_f32_e32 v143, 1.0, v143
	v_rcp_f32_e32 v140, v140
	v_rcp_f32_e32 v141, v141
	v_rcp_f32_e32 v142, v142
	v_rcp_f32_e32 v143, v143
	s_nop 0
	v_pk_mul_f32 v[16:17], v[16:17], v[140:141]
	v_pk_mul_f32 v[18:19], v[18:19], v[142:143]
	v_pk_mul_f32 v[16:17], v[136:137], v[16:17]
	v_pk_mul_f32 v[18:19], v[138:139], v[18:19]
	v_cvt_pk_bf16_f32 v8, v16, v18
	v_cvt_pk_bf16_f32 v9, v17, v19
	global_store_dword v[10:11], v8, off
	global_store_dword v[2:3], v9, off
	v_pk_fma_f32 v[0:1], v[222:223], s[12:13], v[130:131] op_sel_hi:[1,0,0]
	v_add_u32_e32 v8, 50, v168
	v_add_u32_e32 v9, 51, v168
	v_rsq_f32_e32 v0, v0
	v_rsq_f32_e32 v1, v1
	v_mad_i64_i32 v[10:11], s[2:3], v8, s8, v[128:129]
	v_mad_i64_i32 v[2:3], s[2:3], v9, s8, v[128:129]
	v_pk_mul_f32 v[16:17], v[70:71], v[0:1]
	v_pk_mul_f32 v[18:19], v[66:67], v[0:1]
	v_pk_mul_f32 v[136:137], v[78:79], v[0:1]
	v_pk_mul_f32 v[138:139], v[74:75], v[0:1]
	v_mul_f32_e32 v140, 0xbfb8aa3b, v16
	v_mul_f32_e32 v141, 0xbfb8aa3b, v17
	v_mul_f32_e32 v142, 0xbfb8aa3b, v18
	v_mul_f32_e32 v143, 0xbfb8aa3b, v19
	v_exp_f32_e32 v140, v140
	v_exp_f32_e32 v141, v141
	v_exp_f32_e32 v142, v142
	v_exp_f32_e32 v143, v143
	v_add_f32_e32 v140, 1.0, v140
	v_add_f32_e32 v141, 1.0, v141
	v_add_f32_e32 v142, 1.0, v142
	v_add_f32_e32 v143, 1.0, v143
	v_rcp_f32_e32 v140, v140
	v_rcp_f32_e32 v141, v141
	v_rcp_f32_e32 v142, v142
	v_rcp_f32_e32 v143, v143
	s_nop 0
	v_pk_mul_f32 v[16:17], v[16:17], v[140:141]
	v_pk_mul_f32 v[18:19], v[18:19], v[142:143]
	v_pk_mul_f32 v[16:17], v[136:137], v[16:17]
	v_pk_mul_f32 v[18:19], v[138:139], v[18:19]
	v_cvt_pk_bf16_f32 v8, v16, v18
	v_cvt_pk_bf16_f32 v9, v17, v19
	global_store_dword v[10:11], v8, off
	global_store_dword v[2:3], v9, off
	v_pk_fma_f32 v[0:1], v[224:225], s[12:13], v[130:131] op_sel_hi:[1,0,0]
	v_add_u32_e32 v8, 0x80, v168
	v_add_u32_e32 v9, 0x81, v168
	v_rsq_f32_e32 v0, v0
	v_rsq_f32_e32 v1, v1
	v_mad_i64_i32 v[10:11], s[2:3], v8, s8, v[128:129]
	v_mad_i64_i32 v[2:3], s[2:3], v9, s8, v[128:129]
	v_pk_mul_f32 v[16:17], v[52:53], v[0:1]
	v_pk_mul_f32 v[18:19], v[48:49], v[0:1]
	v_pk_mul_f32 v[136:137], v[60:61], v[0:1]
	v_pk_mul_f32 v[138:139], v[56:57], v[0:1]
	v_mul_f32_e32 v140, 0xbfb8aa3b, v16
	v_mul_f32_e32 v141, 0xbfb8aa3b, v17
	v_mul_f32_e32 v142, 0xbfb8aa3b, v18
	v_mul_f32_e32 v143, 0xbfb8aa3b, v19
	v_exp_f32_e32 v140, v140
	v_exp_f32_e32 v141, v141
	v_exp_f32_e32 v142, v142
	v_exp_f32_e32 v143, v143
	v_add_f32_e32 v140, 1.0, v140
	v_add_f32_e32 v141, 1.0, v141
	v_add_f32_e32 v142, 1.0, v142
	v_add_f32_e32 v143, 1.0, v143
	v_rcp_f32_e32 v140, v140
	v_rcp_f32_e32 v141, v141
	v_rcp_f32_e32 v142, v142
	v_rcp_f32_e32 v143, v143
	s_nop 0
	v_pk_mul_f32 v[16:17], v[16:17], v[140:141]
	v_pk_mul_f32 v[18:19], v[18:19], v[142:143]
	v_pk_mul_f32 v[16:17], v[136:137], v[16:17]
	v_pk_mul_f32 v[18:19], v[138:139], v[18:19]
	v_cvt_pk_bf16_f32 v8, v16, v18
	v_cvt_pk_bf16_f32 v9, v17, v19
	global_store_dword v[10:11], v8, off
	global_store_dword v[2:3], v9, off
; __device__ __forceinline__ u32 pack2(float a, float b) { return (u32)f2bf(a) | ((u32)f2bf(b) << 16); }
; __device__ __forceinline__ float sigmoidf_(float x) { return __builtin_amdgcn_rcpf(1.f + __expf(-x)); }
; __device__ __forceinline__ void gemm_tile(const GemmArgs& ga, int wgid, int next_wgid, bool prefetched, u16* shm, unsigned char* ws, int wv_) {
;     ...
;   if (epi == EPI_SWIGLU) {
;     const int oc = pn * HALF + (wc * 16 + fr) * 2;
;     float sc[2][4][4];
;     _Pragma("unroll") for (int ai = 0; ai < 2; ++ai)
;       _Pragma("unroll") for (int m = 0; m < 4; ++m)
;         _Pragma("unroll") for (int j = 0; j < 4; ++j) sc[ai][m][j] = e_ss[rbase + ai * HALF + m * 16 + j];
;     _Pragma("unroll") for (int ai = 0; ai < 2; ++ai)
;       _Pragma("unroll") for (int m = 0; m < 4; ++m)
;         _Pragma("unroll") for (int j = 0; j < 4; ++j) {
;           int row = rbase + ai * HALF + m * 16 + j;
;           float s = rsqrtf(sc[ai][m][j] * (1.f / D_) + 1e-6f);
;           float h2[2];
;           _Pragma("unroll") for (int n = 0; n < 2; ++n) {
;             float a1 = acc[ai][0][m][n][j] * s, a3 = acc[ai][1][m][n][j] * s;
;             h2[n] = a1 * sigmoidf_(a1) * a3;
;           }
;           *(u32*)(e_outb + (size_t)row * F_ + oc) = pack2(h2[0], h2[1]);
;         }
	v_pk_fma_f32 v[0:1], v[226:227], s[12:13], v[130:131] op_sel_hi:[1,0,0]
	v_add_u32_e32 v8, 0x82, v168
	v_add_u32_e32 v9, 0x83, v168
	v_rsq_f32_e32 v0, v0
	v_rsq_f32_e32 v1, v1
	v_mad_i64_i32 v[10:11], s[2:3], v8, s8, v[128:129]
	v_mad_i64_i32 v[2:3], s[2:3], v9, s8, v[128:129]
	v_pk_mul_f32 v[16:17], v[54:55], v[0:1]
	v_pk_mul_f32 v[18:19], v[50:51], v[0:1]
	v_pk_mul_f32 v[136:137], v[62:63], v[0:1]
	v_pk_mul_f32 v[138:139], v[58:59], v[0:1]
	v_mul_f32_e32 v140, 0xbfb8aa3b, v16
	v_mul_f32_e32 v141, 0xbfb8aa3b, v17
	v_mul_f32_e32 v142, 0xbfb8aa3b, v18
	v_mul_f32_e32 v143, 0xbfb8aa3b, v19
	v_exp_f32_e32 v140, v140
	v_exp_f32_e32 v141, v141
	v_exp_f32_e32 v142, v142
	v_exp_f32_e32 v143, v143
	v_add_f32_e32 v140, 1.0, v140
	v_add_f32_e32 v141, 1.0, v141
	v_add_f32_e32 v142, 1.0, v142
	v_add_f32_e32 v143, 1.0, v143
	v_rcp_f32_e32 v140, v140
	v_rcp_f32_e32 v141, v141
	v_rcp_f32_e32 v142, v142
	v_rcp_f32_e32 v143, v143
	s_nop 0
	v_pk_mul_f32 v[16:17], v[16:17], v[140:141]
	v_pk_mul_f32 v[18:19], v[18:19], v[142:143]
	v_pk_mul_f32 v[16:17], v[136:137], v[16:17]
	v_pk_mul_f32 v[18:19], v[138:139], v[18:19]
	v_cvt_pk_bf16_f32 v8, v16, v18
	v_cvt_pk_bf16_f32 v9, v17, v19
	global_store_dword v[10:11], v8, off
	global_store_dword v[2:3], v9, off
	v_pk_fma_f32 v[0:1], v[228:229], s[12:13], v[130:131] op_sel_hi:[1,0,0]
	v_add_u32_e32 v8, 0x90, v168
	v_add_u32_e32 v9, 0x91, v168
	v_rsq_f32_e32 v0, v0
	v_rsq_f32_e32 v1, v1
	v_mad_i64_i32 v[10:11], s[2:3], v8, s8, v[128:129]
	v_mad_i64_i32 v[2:3], s[2:3], v9, s8, v[128:129]
	v_pk_mul_f32 v[16:17], v[36:37], v[0:1]
	v_pk_mul_f32 v[18:19], v[32:33], v[0:1]
	v_pk_mul_f32 v[136:137], v[44:45], v[0:1]
	v_pk_mul_f32 v[138:139], v[40:41], v[0:1]
	v_mul_f32_e32 v140, 0xbfb8aa3b, v16
	v_mul_f32_e32 v141, 0xbfb8aa3b, v17
	v_mul_f32_e32 v142, 0xbfb8aa3b, v18
	v_mul_f32_e32 v143, 0xbfb8aa3b, v19
	v_exp_f32_e32 v140, v140
	v_exp_f32_e32 v141, v141
	v_exp_f32_e32 v142, v142
	v_exp_f32_e32 v143, v143
	v_add_f32_e32 v140, 1.0, v140
	v_add_f32_e32 v141, 1.0, v141
	v_add_f32_e32 v142, 1.0, v142
	v_add_f32_e32 v143, 1.0, v143
	v_rcp_f32_e32 v140, v140
	v_rcp_f32_e32 v141, v141
	v_rcp_f32_e32 v142, v142
	v_rcp_f32_e32 v143, v143
	s_nop 0
	v_pk_mul_f32 v[16:17], v[16:17], v[140:141]
	v_pk_mul_f32 v[18:19], v[18:19], v[142:143]
	v_pk_mul_f32 v[16:17], v[136:137], v[16:17]
	v_pk_mul_f32 v[18:19], v[138:139], v[18:19]
	v_cvt_pk_bf16_f32 v8, v16, v18
	v_cvt_pk_bf16_f32 v9, v17, v19
	global_store_dword v[10:11], v8, off
	global_store_dword v[2:3], v9, off
	v_pk_fma_f32 v[0:1], v[230:231], s[12:13], v[130:131] op_sel_hi:[1,0,0]
	v_add_u32_e32 v8, 0x92, v168
	v_add_u32_e32 v9, 0x93, v168
	v_rsq_f32_e32 v0, v0
	v_rsq_f32_e32 v1, v1
	v_mad_i64_i32 v[10:11], s[2:3], v8, s8, v[128:129]
	v_mad_i64_i32 v[2:3], s[2:3], v9, s8, v[128:129]
	v_pk_mul_f32 v[16:17], v[38:39], v[0:1]
	v_pk_mul_f32 v[18:19], v[34:35], v[0:1]
	v_pk_mul_f32 v[136:137], v[46:47], v[0:1]
	v_pk_mul_f32 v[138:139], v[42:43], v[0:1]
	v_mul_f32_e32 v140, 0xbfb8aa3b, v16
	v_mul_f32_e32 v141, 0xbfb8aa3b, v17
	v_mul_f32_e32 v142, 0xbfb8aa3b, v18
	v_mul_f32_e32 v143, 0xbfb8aa3b, v19
	v_exp_f32_e32 v140, v140
	v_exp_f32_e32 v141, v141
	v_exp_f32_e32 v142, v142
	v_exp_f32_e32 v143, v143
	v_add_f32_e32 v140, 1.0, v140
	v_add_f32_e32 v141, 1.0, v141
	v_add_f32_e32 v142, 1.0, v142
	v_add_f32_e32 v143, 1.0, v143
	v_rcp_f32_e32 v140, v140
	v_rcp_f32_e32 v141, v141
	v_rcp_f32_e32 v142, v142
	v_rcp_f32_e32 v143, v143
	s_nop 0
	v_pk_mul_f32 v[16:17], v[16:17], v[140:141]
	v_pk_mul_f32 v[18:19], v[18:19], v[142:143]
	v_pk_mul_f32 v[16:17], v[136:137], v[16:17]
	v_pk_mul_f32 v[18:19], v[138:139], v[18:19]
	v_cvt_pk_bf16_f32 v8, v16, v18
	v_cvt_pk_bf16_f32 v9, v17, v19
	global_store_dword v[10:11], v8, off
	global_store_dword v[2:3], v9, off
	v_pk_fma_f32 v[0:1], v[232:233], s[12:13], v[130:131] op_sel_hi:[1,0,0]
	v_add_u32_e32 v8, 0xa0, v168
	v_add_u32_e32 v9, 0xa1, v168
	v_rsq_f32_e32 v0, v0
	v_rsq_f32_e32 v1, v1
	v_mad_i64_i32 v[10:11], s[2:3], v8, s8, v[128:129]
	v_mad_i64_i32 v[2:3], s[2:3], v9, s8, v[128:129]
	v_pk_mul_f32 v[16:17], v[20:21], v[0:1]
	v_pk_mul_f32 v[18:19], v[240:241], v[0:1]
	v_pk_mul_f32 v[136:137], v[244:245], v[0:1]
	v_pk_mul_f32 v[138:139], v[24:25], v[0:1]
	v_mul_f32_e32 v140, 0xbfb8aa3b, v16
	v_mul_f32_e32 v141, 0xbfb8aa3b, v17
	v_mul_f32_e32 v142, 0xbfb8aa3b, v18
	v_mul_f32_e32 v143, 0xbfb8aa3b, v19
	v_exp_f32_e32 v140, v140
	v_exp_f32_e32 v141, v141
; __device__ __forceinline__ u32 pack2(float a, float b) { return (u32)f2bf(a) | ((u32)f2bf(b) << 16); }
; __device__ __forceinline__ float sigmoidf_(float x) { return __builtin_amdgcn_rcpf(1.f + __expf(-x)); }
; __device__ __forceinline__ void gemm_tile(const GemmArgs& ga, int wgid, int next_wgid, bool prefetched, u16* shm, unsigned char* ws, int wv_) {
;     ...
;   if (epi == EPI_SWIGLU) {
;     const int oc = pn * HALF + (wc * 16 + fr) * 2;
;     float sc[2][4][4];
;     _Pragma("unroll") for (int ai = 0; ai < 2; ++ai)
;       _Pragma("unroll") for (int m = 0; m < 4; ++m)
;         _Pragma("unroll") for (int j = 0; j < 4; ++j) sc[ai][m][j] = e_ss[rbase + ai * HALF + m * 16 + j];
;     _Pragma("unroll") for (int ai = 0; ai < 2; ++ai)
;       _Pragma("unroll") for (int m = 0; m < 4; ++m)
;         _Pragma("unroll") for (int j = 0; j < 4; ++j) {
;           int row = rbase + ai * HALF + m * 16 + j;
;           float s = rsqrtf(sc[ai][m][j] * (1.f / D_) + 1e-6f);
;           float h2[2];
;           _Pragma("unroll") for (int n = 0; n < 2; ++n) {
;             float a1 = acc[ai][0][m][n][j] * s, a3 = acc[ai][1][m][n][j] * s;
;             h2[n] = a1 * sigmoidf_(a1) * a3;
;           }
;           *(u32*)(e_outb + (size_t)row * F_ + oc) = pack2(h2[0], h2[1]);
;         }
	v_exp_f32_e32 v142, v142
	v_exp_f32_e32 v143, v143
	v_add_f32_e32 v140, 1.0, v140
	v_add_f32_e32 v141, 1.0, v141
	v_add_f32_e32 v142, 1.0, v142
	v_add_f32_e32 v143, 1.0, v143
	v_rcp_f32_e32 v140, v140
	v_rcp_f32_e32 v141, v141
	v_rcp_f32_e32 v142, v142
	v_rcp_f32_e32 v143, v143
	s_nop 0
	v_pk_mul_f32 v[16:17], v[16:17], v[140:141]
	v_pk_mul_f32 v[18:19], v[18:19], v[142:143]
	v_pk_mul_f32 v[16:17], v[136:137], v[16:17]
	v_pk_mul_f32 v[18:19], v[138:139], v[18:19]
	v_cvt_pk_bf16_f32 v8, v16, v18
	v_cvt_pk_bf16_f32 v9, v17, v19
	global_store_dword v[10:11], v8, off
	global_store_dword v[2:3], v9, off
	v_pk_fma_f32 v[0:1], v[234:235], s[12:13], v[130:131] op_sel_hi:[1,0,0]
	v_add_u32_e32 v8, 0xa2, v168
	v_add_u32_e32 v9, 0xa3, v168
	v_rsq_f32_e32 v0, v0
	v_rsq_f32_e32 v1, v1
	v_mad_i64_i32 v[10:11], s[2:3], v8, s8, v[128:129]
	v_mad_i64_i32 v[2:3], s[2:3], v9, s8, v[128:129]
	v_pk_mul_f32 v[16:17], v[22:23], v[0:1]
	v_pk_mul_f32 v[18:19], v[242:243], v[0:1]
	v_pk_mul_f32 v[136:137], v[246:247], v[0:1]
	v_pk_mul_f32 v[138:139], v[26:27], v[0:1]
	v_mul_f32_e32 v140, 0xbfb8aa3b, v16
	v_mul_f32_e32 v141, 0xbfb8aa3b, v17
	v_mul_f32_e32 v142, 0xbfb8aa3b, v18
	v_mul_f32_e32 v143, 0xbfb8aa3b, v19
	v_exp_f32_e32 v140, v140
	v_exp_f32_e32 v141, v141
	v_exp_f32_e32 v142, v142
	v_exp_f32_e32 v143, v143
	v_add_f32_e32 v140, 1.0, v140
	v_add_f32_e32 v141, 1.0, v141
	v_add_f32_e32 v142, 1.0, v142
	v_add_f32_e32 v143, 1.0, v143
	v_rcp_f32_e32 v140, v140
	v_rcp_f32_e32 v141, v141
	v_rcp_f32_e32 v142, v142
	v_rcp_f32_e32 v143, v143
	s_nop 0
	v_pk_mul_f32 v[16:17], v[16:17], v[140:141]
	v_pk_mul_f32 v[18:19], v[18:19], v[142:143]
	v_pk_mul_f32 v[16:17], v[136:137], v[16:17]
	v_pk_mul_f32 v[18:19], v[138:139], v[18:19]
	v_cvt_pk_bf16_f32 v8, v16, v18
	v_cvt_pk_bf16_f32 v9, v17, v19
	global_store_dword v[10:11], v8, off
	global_store_dword v[2:3], v9, off
	v_pk_fma_f32 v[0:1], v[236:237], s[12:13], v[130:131] op_sel_hi:[1,0,0]
	v_add_u32_e32 v8, 0xb0, v168
	v_add_u32_e32 v9, 0xb1, v168
	v_rsq_f32_e32 v0, v0
	v_rsq_f32_e32 v1, v1
	v_mad_i64_i32 v[10:11], s[2:3], v8, s8, v[128:129]
	v_mad_i64_i32 v[2:3], s[2:3], v9, s8, v[128:129]
	v_pk_mul_f32 v[16:17], v[204:205], v[0:1]
	v_pk_mul_f32 v[18:19], v[182:183], v[0:1]
	v_pk_mul_f32 v[136:137], v[12:13], v[0:1]
	v_pk_mul_f32 v[138:139], v[4:5], v[0:1]
	v_mul_f32_e32 v140, 0xbfb8aa3b, v16
	v_mul_f32_e32 v141, 0xbfb8aa3b, v17
	v_mul_f32_e32 v142, 0xbfb8aa3b, v18
	v_mul_f32_e32 v143, 0xbfb8aa3b, v19
	v_exp_f32_e32 v140, v140
	v_exp_f32_e32 v141, v141
	v_exp_f32_e32 v142, v142
	v_exp_f32_e32 v143, v143
	v_add_f32_e32 v140, 1.0, v140
	v_add_f32_e32 v141, 1.0, v141
	v_add_f32_e32 v142, 1.0, v142
	v_add_f32_e32 v143, 1.0, v143
	v_rcp_f32_e32 v140, v140
	v_rcp_f32_e32 v141, v141
	v_rcp_f32_e32 v142, v142
	v_rcp_f32_e32 v143, v143
	s_nop 0
	v_pk_mul_f32 v[16:17], v[16:17], v[140:141]
	v_pk_mul_f32 v[18:19], v[18:19], v[142:143]
	v_pk_mul_f32 v[16:17], v[136:137], v[16:17]
	v_pk_mul_f32 v[18:19], v[138:139], v[18:19]
	v_cvt_pk_bf16_f32 v8, v16, v18
	v_cvt_pk_bf16_f32 v9, v17, v19
	global_store_dword v[10:11], v8, off
	global_store_dword v[2:3], v9, off
	v_pk_fma_f32 v[0:1], v[238:239], s[12:13], v[130:131] op_sel_hi:[1,0,0]
	v_add_u32_e32 v8, 0xb2, v168
	v_add_u32_e32 v9, 0xb3, v168
	v_rsq_f32_e32 v0, v0
	v_rsq_f32_e32 v1, v1
	v_mad_i64_i32 v[10:11], s[2:3], v8, s8, v[128:129]
	v_mad_i64_i32 v[2:3], s[2:3], v9, s8, v[128:129]
	v_pk_mul_f32 v[16:17], v[206:207], v[0:1]
	v_pk_mul_f32 v[18:19], v[184:185], v[0:1]
	v_pk_mul_f32 v[136:137], v[14:15], v[0:1]
	v_pk_mul_f32 v[138:139], v[6:7], v[0:1]
	v_mul_f32_e32 v140, 0xbfb8aa3b, v16
	v_mul_f32_e32 v141, 0xbfb8aa3b, v17
	v_mul_f32_e32 v142, 0xbfb8aa3b, v18
	v_mul_f32_e32 v143, 0xbfb8aa3b, v19
	v_exp_f32_e32 v140, v140
	v_exp_f32_e32 v141, v141
	v_exp_f32_e32 v142, v142
	v_exp_f32_e32 v143, v143
	v_add_f32_e32 v140, 1.0, v140
	v_add_f32_e32 v141, 1.0, v141
	v_add_f32_e32 v142, 1.0, v142
	v_add_f32_e32 v143, 1.0, v143
	v_rcp_f32_e32 v140, v140
	v_rcp_f32_e32 v141, v141
	v_rcp_f32_e32 v142, v142
	v_rcp_f32_e32 v143, v143
	s_nop 0
	v_pk_mul_f32 v[16:17], v[16:17], v[140:141]
	v_pk_mul_f32 v[18:19], v[18:19], v[142:143]
	v_pk_mul_f32 v[16:17], v[136:137], v[16:17]
	v_pk_mul_f32 v[18:19], v[138:139], v[18:19]
	v_cvt_pk_bf16_f32 v8, v16, v18
	v_cvt_pk_bf16_f32 v9, v17, v19
	global_store_dword v[10:11], v8, off
	global_store_dword v[2:3], v9, off
	s_mov_b32 s101, 0x53574947
	s_branch .LBB0_501
